# SEC1 epilogue: counted waits on the rotation-table loads now skip the previous step's stores (vmcnt 3/7 instead of 2)
# speedup vs baseline: 1.0087x; 1.0087x over previous
.Lsec1_a_go:
	s_nop 3
	s_add_u32 s36, s36, s44
	s_addc_u32 s37, s37, 0
	s_add_u32 s40, s40, s44
	s_addc_u32 s41, s41, 0
	s_add_u32 s4, s4, s45
	s_addc_u32 s5, s5, 0
	v_add_u32_e32 v222, 0x11000, v221
	global_load_dwordx4 v[188:191], v234, s[4:5]
	global_load_dwordx4 v[192:195], v234, s[4:5] offset:16
	s_waitcnt vmcnt(2)
	v_mul_f32_e32 v132, 0x3fb8aa3b, v132
	v_exp_f32_e32 v132, v132
	v_mul_f32_e32 v133, 0x3fb8aa3b, v133
	v_exp_f32_e32 v133, v133
	v_sub_u32_e32 v156, 0x7f, v134
	v_cvt_f32_u32_e32 v156, v156
	v_mul_f32_e64 v156, v156, -v132
	v_mul_f32_e32 v156, 0x3fb8aa3b, v156
	v_exp_f32_e32 v156, v156
	v_cvt_f32_u32_e32 v160, v134
	v_mul_f32_e64 v160, v160, -v133
	v_mul_f32_e32 v160, 0x3fb8aa3b, v160
	v_exp_f32_e32 v160, v160
	v_add_u32_e32 v134, s3, v134
	v_sub_u32_e32 v157, 0x7f, v134
	v_cvt_f32_u32_e32 v157, v157
	v_mul_f32_e64 v157, v157, -v132
	v_mul_f32_e32 v157, 0x3fb8aa3b, v157
	v_exp_f32_e32 v157, v157
	v_cvt_f32_u32_e32 v161, v134
	v_mul_f32_e64 v161, v161, -v133
	v_mul_f32_e32 v161, 0x3fb8aa3b, v161
	v_exp_f32_e32 v161, v161
	v_add_u32_e32 v134, s3, v134
	v_sub_u32_e32 v158, 0x7f, v134
	v_cvt_f32_u32_e32 v158, v158
	v_mul_f32_e64 v158, v158, -v132
	v_mul_f32_e32 v158, 0x3fb8aa3b, v158
	v_exp_f32_e32 v158, v158
	v_cvt_f32_u32_e32 v162, v134
	v_mul_f32_e64 v162, v162, -v133
	v_mul_f32_e32 v162, 0x3fb8aa3b, v162
	v_exp_f32_e32 v162, v162
	v_add_u32_e32 v134, s3, v134
	v_sub_u32_e32 v159, 0x7f, v134
	v_cvt_f32_u32_e32 v159, v159
	v_mul_f32_e64 v159, v159, -v132
	v_mul_f32_e32 v159, 0x3fb8aa3b, v159
	v_exp_f32_e32 v159, v159
	v_cvt_f32_u32_e32 v163, v134
	v_mul_f32_e64 v163, v163, -v133
	v_mul_f32_e32 v163, 0x3fb8aa3b, v163
	v_exp_f32_e32 v163, v163
	s_add_u32 s4, s4, s21
	s_addc_u32 s5, s5, 0
	global_load_dwordx4 v[196:199], v234, s[4:5]
	global_load_dwordx4 v[200:203], v234, s[4:5] offset:16
	s_waitcnt vmcnt(2)
	v_mul_f32_e32 v132, v164, v128
	v_mul_f32_e32 v133, v164, v129
	v_mul_f32_e32 v134, v164, v130
	v_mul_f32_e32 v135, v164, v131
	v_mul_f32_e32 v136, v164, v124
	v_mul_f32_e32 v137, v164, v125
	v_mul_f32_e32 v138, v164, v126
	v_mul_f32_e32 v139, v164, v127
	v_mul_f32_e32 v235, v189, v133
	v_mul_f32_e32 v236, v189, v132
	v_fma_f32 v132, v188, v132, -v235
	v_fma_f32 v133, v188, v133, v236
	v_mul_f32_e32 v235, v191, v135
	v_mul_f32_e32 v236, v191, v134
	v_fma_f32 v134, v190, v134, -v235
	v_fma_f32 v135, v190, v135, v236
	v_mul_f32_e32 v235, v193, v137
	v_mul_f32_e32 v236, v193, v136
	v_fma_f32 v136, v192, v136, -v235
	v_fma_f32 v137, v192, v137, v236
	v_mul_f32_e32 v235, v195, v139
	v_mul_f32_e32 v236, v195, v138
	v_fma_f32 v138, v194, v138, -v235
	v_fma_f32 v139, v194, v139, v236
	v_cvt_pk_bf16_f32 v204, v132, v133
	v_cvt_pk_bf16_f32 v205, v134, v135
	v_cvt_pk_bf16_f32 v206, v136, v137
	v_cvt_pk_bf16_f32 v207, v138, v139
	global_store_dwordx4 v223, v[204:207], s[16:17]
	s_add_u32 s16, s16, 0x4000
	s_addc_u32 s17, s17, 0
	v_mul_f32_e32 v235, v156, v132
	v_mul_f32_e32 v236, v156, v133
	v_cvt_pk_bf16_f32 v208, v235, v236
	v_mul_f32_e32 v235, v156, v134
	v_mul_f32_e32 v236, v156, v135
	v_cvt_pk_bf16_f32 v209, v235, v236
	v_mul_f32_e32 v235, v156, v136
	v_mul_f32_e32 v236, v156, v137
	v_cvt_pk_bf16_f32 v210, v235, v236
	v_mul_f32_e32 v235, v156, v138
	v_mul_f32_e32 v236, v156, v139
	v_cvt_pk_bf16_f32 v211, v235, v236
	ds_write_b128 v168, v[208:211]
	v_mul_f32_e32 v235, v160, v132
	v_mul_f32_e32 v236, v160, v133
	v_cvt_pk_bf16_f32 v140, v235, v236
	v_mul_f32_e32 v235, v160, v134
	v_mul_f32_e32 v236, v160, v135
	v_cvt_pk_bf16_f32 v141, v235, v236
	v_mul_f32_e32 v235, v160, v136
	v_mul_f32_e32 v236, v160, v137
	v_cvt_pk_bf16_f32 v142, v235, v236
	v_mul_f32_e32 v235, v160, v138
	v_mul_f32_e32 v236, v160, v139
	v_cvt_pk_bf16_f32 v143, v235, v236
	s_add_u32 s4, s4, s21
	s_addc_u32 s5, s5, 0
	global_load_dwordx4 v[188:191], v234, s[4:5]
	global_load_dwordx4 v[192:195], v234, s[4:5] offset:16
	s_waitcnt vmcnt(3)
	v_mul_f32_e32 v132, v165, v120
	v_mul_f32_e32 v133, v165, v121
	v_mul_f32_e32 v134, v165, v122
	v_mul_f32_e32 v135, v165, v123
	v_mul_f32_e32 v136, v165, v116
	v_mul_f32_e32 v137, v165, v117
	v_mul_f32_e32 v138, v165, v118
	v_mul_f32_e32 v139, v165, v119
	v_mul_f32_e32 v235, v197, v133
	v_mul_f32_e32 v236, v197, v132
	v_fma_f32 v132, v196, v132, -v235
	v_fma_f32 v133, v196, v133, v236
	v_mul_f32_e32 v235, v199, v135
	v_mul_f32_e32 v236, v199, v134
	v_fma_f32 v134, v198, v134, -v235
	v_fma_f32 v135, v198, v135, v236
	v_mul_f32_e32 v235, v201, v137
	v_mul_f32_e32 v236, v201, v136
	v_fma_f32 v136, v200, v136, -v235
	v_fma_f32 v137, v200, v137, v236
	v_mul_f32_e32 v235, v203, v139
	v_mul_f32_e32 v236, v203, v138
	v_fma_f32 v138, v202, v138, -v235
	v_fma_f32 v139, v202, v139, v236
	v_cvt_pk_bf16_f32 v204, v132, v133
	v_cvt_pk_bf16_f32 v205, v134, v135
	v_cvt_pk_bf16_f32 v206, v136, v137
	v_cvt_pk_bf16_f32 v207, v138, v139
	global_store_dwordx4 v223, v[204:207], s[16:17]
	s_add_u32 s16, s16, 0x4000
	s_addc_u32 s17, s17, 0
	v_mul_f32_e32 v235, v157, v132
	v_mul_f32_e32 v236, v157, v133
	v_cvt_pk_bf16_f32 v208, v235, v236
	v_mul_f32_e32 v235, v157, v134
	v_mul_f32_e32 v236, v157, v135
	v_cvt_pk_bf16_f32 v209, v235, v236
	v_mul_f32_e32 v235, v157, v136
	v_mul_f32_e32 v236, v157, v137
	v_cvt_pk_bf16_f32 v210, v235, v236
	v_mul_f32_e32 v235, v157, v138
	v_mul_f32_e32 v236, v157, v139
	v_cvt_pk_bf16_f32 v211, v235, v236
	ds_write_b128 v168, v[208:211] offset:1024
	v_mul_f32_e32 v235, v161, v132
	v_mul_f32_e32 v236, v161, v133
	v_cvt_pk_bf16_f32 v144, v235, v236
	v_mul_f32_e32 v235, v161, v134
	v_mul_f32_e32 v236, v161, v135
	v_cvt_pk_bf16_f32 v145, v235, v236
	v_mul_f32_e32 v235, v161, v136
	v_mul_f32_e32 v236, v161, v137
	v_cvt_pk_bf16_f32 v146, v235, v236
	v_mul_f32_e32 v235, v161, v138
	v_mul_f32_e32 v236, v161, v139
	v_cvt_pk_bf16_f32 v147, v235, v236
	ds_read_b64_tr_b16 v[204:205], v169
	ds_read_b64_tr_b16 v[206:207], v169 offset:256
	ds_read_b64_tr_b16 v[208:209], v220
	ds_read_b64_tr_b16 v[210:211], v220 offset:256
	s_waitcnt lgkmcnt(0)
	global_store_dwordx4 v221, v[204:207], s[36:37]
	global_store_dwordx4 v222, v[208:211], s[36:37]
	ds_write_b128 v168, v[140:143]
	ds_write_b128 v168, v[144:147] offset:1024
	s_nop 1
	ds_read_b64_tr_b16 v[204:205], v169
	ds_read_b64_tr_b16 v[206:207], v169 offset:256
	ds_read_b64_tr_b16 v[208:209], v220
	ds_read_b64_tr_b16 v[210:211], v220 offset:256
	s_waitcnt lgkmcnt(0)
	global_store_dwordx4 v221, v[204:207], s[40:41]
	global_store_dwordx4 v222, v[208:211], s[40:41]
	s_add_u32 s36, s36, s43
	s_addc_u32 s37, s37, 0
	s_add_u32 s40, s40, s43
	s_addc_u32 s41, s41, 0
	s_add_u32 s4, s4, s21
	s_addc_u32 s5, s5, 0
	global_load_dwordx4 v[196:199], v234, s[4:5]
	global_load_dwordx4 v[200:203], v234, s[4:5] offset:16
	s_waitcnt vmcnt(7)
	v_mul_f32_e32 v132, v166, v112
	v_mul_f32_e32 v133, v166, v113
	v_mul_f32_e32 v134, v166, v114
	v_mul_f32_e32 v135, v166, v115
	v_mul_f32_e32 v136, v166, v108
	v_mul_f32_e32 v137, v166, v109
	v_mul_f32_e32 v138, v166, v110
	v_mul_f32_e32 v139, v166, v111
	v_mul_f32_e32 v235, v189, v133
	v_mul_f32_e32 v236, v189, v132
	v_fma_f32 v132, v188, v132, -v235
	v_fma_f32 v133, v188, v133, v236
	v_mul_f32_e32 v235, v191, v135
	v_mul_f32_e32 v236, v191, v134
	v_fma_f32 v134, v190, v134, -v235
	v_fma_f32 v135, v190, v135, v236
	v_mul_f32_e32 v235, v193, v137
	v_mul_f32_e32 v236, v193, v136
	v_fma_f32 v136, v192, v136, -v235
	v_fma_f32 v137, v192, v137, v236
	v_mul_f32_e32 v235, v195, v139
	v_mul_f32_e32 v236, v195, v138
	v_fma_f32 v138, v194, v138, -v235
	v_fma_f32 v139, v194, v139, v236
	v_cvt_pk_bf16_f32 v204, v132, v133
	v_cvt_pk_bf16_f32 v205, v134, v135
	v_cvt_pk_bf16_f32 v206, v136, v137
	v_cvt_pk_bf16_f32 v207, v138, v139
	global_store_dwordx4 v223, v[204:207], s[16:17]
	s_add_u32 s16, s16, 0x4000
	s_addc_u32 s17, s17, 0
	v_mul_f32_e32 v235, v158, v132
	v_mul_f32_e32 v236, v158, v133
	v_cvt_pk_bf16_f32 v208, v235, v236
	v_mul_f32_e32 v235, v158, v134
	v_mul_f32_e32 v236, v158, v135
	v_cvt_pk_bf16_f32 v209, v235, v236
	v_mul_f32_e32 v235, v158, v136
	v_mul_f32_e32 v236, v158, v137
	v_cvt_pk_bf16_f32 v210, v235, v236
	v_mul_f32_e32 v235, v158, v138
	v_mul_f32_e32 v236, v158, v139
	v_cvt_pk_bf16_f32 v211, v235, v236
	ds_write_b128 v168, v[208:211]
	v_mul_f32_e32 v235, v162, v132
	v_mul_f32_e32 v236, v162, v133
	v_cvt_pk_bf16_f32 v140, v235, v236
	v_mul_f32_e32 v235, v162, v134
	v_mul_f32_e32 v236, v162, v135
	v_cvt_pk_bf16_f32 v141, v235, v236
	v_mul_f32_e32 v235, v162, v136
	v_mul_f32_e32 v236, v162, v137
	v_cvt_pk_bf16_f32 v142, v235, v236
	v_mul_f32_e32 v235, v162, v138
	v_mul_f32_e32 v236, v162, v139
	v_cvt_pk_bf16_f32 v143, v235, v236
	s_add_u32 s4, s4, 0x5000
	s_addc_u32 s5, s5, 0
	global_load_dwordx4 v[188:191], v234, s[4:5]
	global_load_dwordx4 v[192:195], v234, s[4:5] offset:16
	s_waitcnt vmcnt(3)
	v_mul_f32_e32 v132, v167, v104
	v_mul_f32_e32 v133, v167, v105
	v_mul_f32_e32 v134, v167, v106
	v_mul_f32_e32 v135, v167, v107
	v_mul_f32_e32 v136, v167, v100
	v_mul_f32_e32 v137, v167, v101
	v_mul_f32_e32 v138, v167, v102
	v_mul_f32_e32 v139, v167, v103
	v_mul_f32_e32 v235, v197, v133
	v_mul_f32_e32 v236, v197, v132
	v_fma_f32 v132, v196, v132, -v235
	v_fma_f32 v133, v196, v133, v236
	v_mul_f32_e32 v235, v199, v135
	v_mul_f32_e32 v236, v199, v134
	v_fma_f32 v134, v198, v134, -v235
	v_fma_f32 v135, v198, v135, v236
	v_mul_f32_e32 v235, v201, v137
	v_mul_f32_e32 v236, v201, v136
	v_fma_f32 v136, v200, v136, -v235
	v_fma_f32 v137, v200, v137, v236
	v_mul_f32_e32 v235, v203, v139
	v_mul_f32_e32 v236, v203, v138
	v_fma_f32 v138, v202, v138, -v235
	v_fma_f32 v139, v202, v139, v236
	v_cvt_pk_bf16_f32 v204, v132, v133
	v_cvt_pk_bf16_f32 v205, v134, v135
	v_cvt_pk_bf16_f32 v206, v136, v137
	v_cvt_pk_bf16_f32 v207, v138, v139
	global_store_dwordx4 v223, v[204:207], s[16:17]
	s_add_u32 s16, s16, 0x14000
	s_addc_u32 s17, s17, 0
	v_mul_f32_e32 v235, v159, v132
	v_mul_f32_e32 v236, v159, v133
	v_cvt_pk_bf16_f32 v208, v235, v236
	v_mul_f32_e32 v235, v159, v134
	v_mul_f32_e32 v236, v159, v135
	v_cvt_pk_bf16_f32 v209, v235, v236
	v_mul_f32_e32 v235, v159, v136
	v_mul_f32_e32 v236, v159, v137
	v_cvt_pk_bf16_f32 v210, v235, v236
	v_mul_f32_e32 v235, v159, v138
	v_mul_f32_e32 v236, v159, v139
	v_cvt_pk_bf16_f32 v211, v235, v236
	ds_write_b128 v168, v[208:211] offset:1024
	v_mul_f32_e32 v235, v163, v132
	v_mul_f32_e32 v236, v163, v133
	v_cvt_pk_bf16_f32 v144, v235, v236
	v_mul_f32_e32 v235, v163, v134
	v_mul_f32_e32 v236, v163, v135
	v_cvt_pk_bf16_f32 v145, v235, v236
	v_mul_f32_e32 v235, v163, v136
	v_mul_f32_e32 v236, v163, v137
	v_cvt_pk_bf16_f32 v146, v235, v236
	v_mul_f32_e32 v235, v163, v138
	v_mul_f32_e32 v236, v163, v139
	v_cvt_pk_bf16_f32 v147, v235, v236
	ds_read_b64_tr_b16 v[204:205], v169
	ds_read_b64_tr_b16 v[206:207], v169 offset:256
	ds_read_b64_tr_b16 v[208:209], v220
	ds_read_b64_tr_b16 v[210:211], v220 offset:256
	s_waitcnt lgkmcnt(0)
	global_store_dwordx4 v221, v[204:207], s[36:37]
	global_store_dwordx4 v222, v[208:211], s[36:37]
	ds_write_b128 v168, v[140:143]
	ds_write_b128 v168, v[144:147] offset:1024
	s_nop 1
	ds_read_b64_tr_b16 v[204:205], v169
	ds_read_b64_tr_b16 v[206:207], v169 offset:256
	ds_read_b64_tr_b16 v[208:209], v220
	ds_read_b64_tr_b16 v[210:211], v220 offset:256
	s_waitcnt lgkmcnt(0)
	global_store_dwordx4 v221, v[204:207], s[40:41]
	global_store_dwordx4 v222, v[208:211], s[40:41]
	s_add_u32 s36, s36, 0xc0
	s_addc_u32 s37, s37, 0
	s_add_u32 s40, s40, 0xc0
	s_addc_u32 s41, s41, 0
	s_cmp_eq_u32 s48, 64
	s_cbranch_scc1 .Lsec1_a_done
	s_add_u32 s4, s4, s21
	s_addc_u32 s5, s5, 0
	global_load_dwordx4 v[196:199], v234, s[4:5]
	global_load_dwordx4 v[200:203], v234, s[4:5] offset:16
	s_waitcnt vmcnt(7)
	v_mul_f32_e32 v132, v246, v96
	v_mul_f32_e32 v133, v246, v97
	v_mul_f32_e32 v134, v246, v98
	v_mul_f32_e32 v135, v246, v99
	v_mul_f32_e32 v136, v246, v92
	v_mul_f32_e32 v137, v246, v93
	v_mul_f32_e32 v138, v246, v94
	v_mul_f32_e32 v139, v246, v95
	v_mul_f32_e32 v235, v189, v133
	v_mul_f32_e32 v236, v189, v132
	v_fma_f32 v132, v188, v132, -v235
	v_fma_f32 v133, v188, v133, v236
	v_mul_f32_e32 v235, v191, v135
	v_mul_f32_e32 v236, v191, v134
	v_fma_f32 v134, v190, v134, -v235
	v_fma_f32 v135, v190, v135, v236
	v_mul_f32_e32 v235, v193, v137
	v_mul_f32_e32 v236, v193, v136
	v_fma_f32 v136, v192, v136, -v235
	v_fma_f32 v137, v192, v137, v236
	v_mul_f32_e32 v235, v195, v139
	v_mul_f32_e32 v236, v195, v138
	v_fma_f32 v138, v194, v138, -v235
	v_fma_f32 v139, v194, v139, v236
	v_cvt_pk_bf16_f32 v204, v132, v133
	v_cvt_pk_bf16_f32 v205, v134, v135
	v_cvt_pk_bf16_f32 v206, v136, v137
	v_cvt_pk_bf16_f32 v207, v138, v139
	global_store_dwordx4 v223, v[204:207], s[16:17]
	s_add_u32 s16, s16, 0x4000
	s_addc_u32 s17, s17, 0
	v_mul_f32_e32 v235, v156, v132
	v_mul_f32_e32 v236, v156, v133
	v_cvt_pk_bf16_f32 v208, v235, v236
	v_mul_f32_e32 v235, v156, v134
	v_mul_f32_e32 v236, v156, v135
	v_cvt_pk_bf16_f32 v209, v235, v236
	v_mul_f32_e32 v235, v156, v136
	v_mul_f32_e32 v236, v156, v137
	v_cvt_pk_bf16_f32 v210, v235, v236
	v_mul_f32_e32 v235, v156, v138
	v_mul_f32_e32 v236, v156, v139
	v_cvt_pk_bf16_f32 v211, v235, v236
	ds_write_b128 v168, v[208:211]
	v_mul_f32_e32 v235, v160, v132
	v_mul_f32_e32 v236, v160, v133
	v_cvt_pk_bf16_f32 v140, v235, v236
	v_mul_f32_e32 v235, v160, v134
	v_mul_f32_e32 v236, v160, v135
	v_cvt_pk_bf16_f32 v141, v235, v236
	v_mul_f32_e32 v235, v160, v136
	v_mul_f32_e32 v236, v160, v137
	v_cvt_pk_bf16_f32 v142, v235, v236
	v_mul_f32_e32 v235, v160, v138
	v_mul_f32_e32 v236, v160, v139
	v_cvt_pk_bf16_f32 v143, v235, v236
	s_add_u32 s4, s4, s21
	s_addc_u32 s5, s5, 0
	global_load_dwordx4 v[188:191], v234, s[4:5]
	global_load_dwordx4 v[192:195], v234, s[4:5] offset:16
	s_waitcnt vmcnt(3)
	v_mul_f32_e32 v132, v247, v88
	v_mul_f32_e32 v133, v247, v89
	v_mul_f32_e32 v134, v247, v90
	v_mul_f32_e32 v135, v247, v91
	v_mul_f32_e32 v136, v247, v84
	v_mul_f32_e32 v137, v247, v85
	v_mul_f32_e32 v138, v247, v86
	v_mul_f32_e32 v139, v247, v87
	v_mul_f32_e32 v235, v197, v133
	v_mul_f32_e32 v236, v197, v132
	v_fma_f32 v132, v196, v132, -v235
	v_fma_f32 v133, v196, v133, v236
	v_mul_f32_e32 v235, v199, v135
	v_mul_f32_e32 v236, v199, v134
	v_fma_f32 v134, v198, v134, -v235
	v_fma_f32 v135, v198, v135, v236
	v_mul_f32_e32 v235, v201, v137
	v_mul_f32_e32 v236, v201, v136
	v_fma_f32 v136, v200, v136, -v235
	v_fma_f32 v137, v200, v137, v236
	v_mul_f32_e32 v235, v203, v139
	v_mul_f32_e32 v236, v203, v138
	v_fma_f32 v138, v202, v138, -v235
	v_fma_f32 v139, v202, v139, v236
	v_cvt_pk_bf16_f32 v204, v132, v133
	v_cvt_pk_bf16_f32 v205, v134, v135
	v_cvt_pk_bf16_f32 v206, v136, v137
	v_cvt_pk_bf16_f32 v207, v138, v139
	global_store_dwordx4 v223, v[204:207], s[16:17]
	s_add_u32 s16, s16, 0x4000
	s_addc_u32 s17, s17, 0
	v_mul_f32_e32 v235, v157, v132
	v_mul_f32_e32 v236, v157, v133
	v_cvt_pk_bf16_f32 v208, v235, v236
	v_mul_f32_e32 v235, v157, v134
	v_mul_f32_e32 v236, v157, v135
	v_cvt_pk_bf16_f32 v209, v235, v236
	v_mul_f32_e32 v235, v157, v136
	v_mul_f32_e32 v236, v157, v137
	v_cvt_pk_bf16_f32 v210, v235, v236
	v_mul_f32_e32 v235, v157, v138
	v_mul_f32_e32 v236, v157, v139
	v_cvt_pk_bf16_f32 v211, v235, v236
	ds_write_b128 v168, v[208:211] offset:1024
	v_mul_f32_e32 v235, v161, v132
	v_mul_f32_e32 v236, v161, v133
	v_cvt_pk_bf16_f32 v144, v235, v236
	v_mul_f32_e32 v235, v161, v134
	v_mul_f32_e32 v236, v161, v135
	v_cvt_pk_bf16_f32 v145, v235, v236
	v_mul_f32_e32 v235, v161, v136
	v_mul_f32_e32 v236, v161, v137
	v_cvt_pk_bf16_f32 v146, v235, v236
	v_mul_f32_e32 v235, v161, v138
	v_mul_f32_e32 v236, v161, v139
	v_cvt_pk_bf16_f32 v147, v235, v236
	ds_read_b64_tr_b16 v[204:205], v169
	ds_read_b64_tr_b16 v[206:207], v169 offset:256
	ds_read_b64_tr_b16 v[208:209], v220
	ds_read_b64_tr_b16 v[210:211], v220 offset:256
	s_waitcnt lgkmcnt(0)
	global_store_dwordx4 v221, v[204:207], s[36:37]
	global_store_dwordx4 v222, v[208:211], s[36:37]
	ds_write_b128 v168, v[140:143]
	ds_write_b128 v168, v[144:147] offset:1024
	s_nop 1
	ds_read_b64_tr_b16 v[204:205], v169
	ds_read_b64_tr_b16 v[206:207], v169 offset:256
	ds_read_b64_tr_b16 v[208:209], v220
	ds_read_b64_tr_b16 v[210:211], v220 offset:256
	s_waitcnt lgkmcnt(0)
	global_store_dwordx4 v221, v[204:207], s[40:41]
	global_store_dwordx4 v222, v[208:211], s[40:41]
	s_add_u32 s36, s36, 64
	s_addc_u32 s37, s37, 0
	s_add_u32 s40, s40, 64
	s_addc_u32 s41, s41, 0
	s_add_u32 s4, s4, s21
	s_addc_u32 s5, s5, 0
	global_load_dwordx4 v[196:199], v234, s[4:5]
	global_load_dwordx4 v[200:203], v234, s[4:5] offset:16
	s_waitcnt vmcnt(7)
	v_mul_f32_e32 v132, v248, v80
	v_mul_f32_e32 v133, v248, v81
	v_mul_f32_e32 v134, v248, v82
	v_mul_f32_e32 v135, v248, v83
	v_mul_f32_e32 v136, v248, v76
	v_mul_f32_e32 v137, v248, v77
	v_mul_f32_e32 v138, v248, v78
	v_mul_f32_e32 v139, v248, v79
	v_mul_f32_e32 v235, v189, v133
	v_mul_f32_e32 v236, v189, v132
	v_fma_f32 v132, v188, v132, -v235
	v_fma_f32 v133, v188, v133, v236
	v_mul_f32_e32 v235, v191, v135
	v_mul_f32_e32 v236, v191, v134
	v_fma_f32 v134, v190, v134, -v235
	v_fma_f32 v135, v190, v135, v236
	v_mul_f32_e32 v235, v193, v137
	v_mul_f32_e32 v236, v193, v136
	v_fma_f32 v136, v192, v136, -v235
	v_fma_f32 v137, v192, v137, v236
	v_mul_f32_e32 v235, v195, v139
	v_mul_f32_e32 v236, v195, v138
	v_fma_f32 v138, v194, v138, -v235
	v_fma_f32 v139, v194, v139, v236
	v_cvt_pk_bf16_f32 v204, v132, v133
	v_cvt_pk_bf16_f32 v205, v134, v135
	v_cvt_pk_bf16_f32 v206, v136, v137
	v_cvt_pk_bf16_f32 v207, v138, v139
	global_store_dwordx4 v223, v[204:207], s[16:17]
	s_add_u32 s16, s16, 0x4000
	s_addc_u32 s17, s17, 0
	v_mul_f32_e32 v235, v158, v132
	v_mul_f32_e32 v236, v158, v133
	v_cvt_pk_bf16_f32 v208, v235, v236
	v_mul_f32_e32 v235, v158, v134
	v_mul_f32_e32 v236, v158, v135
	v_cvt_pk_bf16_f32 v209, v235, v236
	v_mul_f32_e32 v235, v158, v136
	v_mul_f32_e32 v236, v158, v137
	v_cvt_pk_bf16_f32 v210, v235, v236
	v_mul_f32_e32 v235, v158, v138
	v_mul_f32_e32 v236, v158, v139
	v_cvt_pk_bf16_f32 v211, v235, v236
	ds_write_b128 v168, v[208:211]
	v_mul_f32_e32 v235, v162, v132
	v_mul_f32_e32 v236, v162, v133
	v_cvt_pk_bf16_f32 v140, v235, v236
	v_mul_f32_e32 v235, v162, v134
	v_mul_f32_e32 v236, v162, v135
	v_cvt_pk_bf16_f32 v141, v235, v236
	v_mul_f32_e32 v235, v162, v136
	v_mul_f32_e32 v236, v162, v137
	v_cvt_pk_bf16_f32 v142, v235, v236
	v_mul_f32_e32 v235, v162, v138
	v_mul_f32_e32 v236, v162, v139
	v_cvt_pk_bf16_f32 v143, v235, v236
	s_waitcnt vmcnt(1)
	v_mul_f32_e32 v132, v249, v72
	v_mul_f32_e32 v133, v249, v73
	v_mul_f32_e32 v134, v249, v74
	v_mul_f32_e32 v135, v249, v75
	v_mul_f32_e32 v136, v249, v68
	v_mul_f32_e32 v137, v249, v69
	v_mul_f32_e32 v138, v249, v70
	v_mul_f32_e32 v139, v249, v71
	v_mul_f32_e32 v235, v197, v133
	v_mul_f32_e32 v236, v197, v132
	v_fma_f32 v132, v196, v132, -v235
	v_fma_f32 v133, v196, v133, v236
	v_mul_f32_e32 v235, v199, v135
	v_mul_f32_e32 v236, v199, v134
	v_fma_f32 v134, v198, v134, -v235
	v_fma_f32 v135, v198, v135, v236
	v_mul_f32_e32 v235, v201, v137
	v_mul_f32_e32 v236, v201, v136
	v_fma_f32 v136, v200, v136, -v235
	v_fma_f32 v137, v200, v137, v236
	v_mul_f32_e32 v235, v203, v139
	v_mul_f32_e32 v236, v203, v138
	v_fma_f32 v138, v202, v138, -v235
	v_fma_f32 v139, v202, v139, v236
	v_cvt_pk_bf16_f32 v204, v132, v133
	v_cvt_pk_bf16_f32 v205, v134, v135
	v_cvt_pk_bf16_f32 v206, v136, v137
	v_cvt_pk_bf16_f32 v207, v138, v139
	global_store_dwordx4 v223, v[204:207], s[16:17]
	s_add_u32 s16, s16, 0x14000
	s_addc_u32 s17, s17, 0
	v_mul_f32_e32 v235, v159, v132
	v_mul_f32_e32 v236, v159, v133
	v_cvt_pk_bf16_f32 v208, v235, v236
	v_mul_f32_e32 v235, v159, v134
	v_mul_f32_e32 v236, v159, v135
	v_cvt_pk_bf16_f32 v209, v235, v236
	v_mul_f32_e32 v235, v159, v136
	v_mul_f32_e32 v236, v159, v137
	v_cvt_pk_bf16_f32 v210, v235, v236
	v_mul_f32_e32 v235, v159, v138
	v_mul_f32_e32 v236, v159, v139
	v_cvt_pk_bf16_f32 v211, v235, v236
	ds_write_b128 v168, v[208:211] offset:1024
	v_mul_f32_e32 v235, v163, v132
	v_mul_f32_e32 v236, v163, v133
	v_cvt_pk_bf16_f32 v144, v235, v236
	v_mul_f32_e32 v235, v163, v134
	v_mul_f32_e32 v236, v163, v135
	v_cvt_pk_bf16_f32 v145, v235, v236
	v_mul_f32_e32 v235, v163, v136
	v_mul_f32_e32 v236, v163, v137
	v_cvt_pk_bf16_f32 v146, v235, v236
	v_mul_f32_e32 v235, v163, v138
	v_mul_f32_e32 v236, v163, v139
	v_cvt_pk_bf16_f32 v147, v235, v236
	ds_read_b64_tr_b16 v[204:205], v169
	ds_read_b64_tr_b16 v[206:207], v169 offset:256
	ds_read_b64_tr_b16 v[208:209], v220
	ds_read_b64_tr_b16 v[210:211], v220 offset:256
	s_waitcnt lgkmcnt(0)
	global_store_dwordx4 v221, v[204:207], s[36:37]
	global_store_dwordx4 v222, v[208:211], s[36:37]
	ds_write_b128 v168, v[140:143]
	ds_write_b128 v168, v[144:147] offset:1024
	s_nop 1
	ds_read_b64_tr_b16 v[204:205], v169
	ds_read_b64_tr_b16 v[206:207], v169 offset:256
	ds_read_b64_tr_b16 v[208:209], v220
	ds_read_b64_tr_b16 v[210:211], v220 offset:256
	s_waitcnt lgkmcnt(0)
	global_store_dwordx4 v221, v[204:207], s[40:41]
	global_store_dwordx4 v222, v[208:211], s[40:41]

.Lsec1_b_go:
	s_nop 3
	s_add_u32 s36, s36, s44
	s_addc_u32 s37, s37, 0
	s_add_u32 s40, s40, s44
	s_addc_u32 s41, s41, 0
	s_add_u32 s4, s4, s45
	s_addc_u32 s5, s5, 0
	v_add_u32_e32 v88, 0x11000, v87
	global_load_dwordx4 v[92:95], v90, s[4:5]
	global_load_dwordx4 v[96:99], v90, s[4:5] offset:16
	s_waitcnt vmcnt(2)
	v_mul_f32_e32 v108, 0x3fb8aa3b, v108
	v_exp_f32_e32 v108, v108
	v_mul_f32_e32 v109, 0x3fb8aa3b, v109
	v_exp_f32_e32 v109, v109
	v_sub_u32_e32 v76, 0x7f, v110
	v_cvt_f32_u32_e32 v76, v76
	v_mul_f32_e64 v76, v76, -v108
	v_mul_f32_e32 v76, 0x3fb8aa3b, v76
	v_exp_f32_e32 v76, v76
	v_cvt_f32_u32_e32 v80, v110
	v_mul_f32_e64 v80, v80, -v109
	v_mul_f32_e32 v80, 0x3fb8aa3b, v80
	v_exp_f32_e32 v80, v80
	v_add_u32_e32 v110, s3, v110
	v_sub_u32_e32 v77, 0x7f, v110
	v_cvt_f32_u32_e32 v77, v77
	v_mul_f32_e64 v77, v77, -v108
	v_mul_f32_e32 v77, 0x3fb8aa3b, v77
	v_exp_f32_e32 v77, v77
	v_cvt_f32_u32_e32 v81, v110
	v_mul_f32_e64 v81, v81, -v109
	v_mul_f32_e32 v81, 0x3fb8aa3b, v81
	v_exp_f32_e32 v81, v81
	v_add_u32_e32 v110, s3, v110
	v_sub_u32_e32 v78, 0x7f, v110
	v_cvt_f32_u32_e32 v78, v78
	v_mul_f32_e64 v78, v78, -v108
	v_mul_f32_e32 v78, 0x3fb8aa3b, v78
	v_exp_f32_e32 v78, v78
	v_cvt_f32_u32_e32 v82, v110
	v_mul_f32_e64 v82, v82, -v109
	v_mul_f32_e32 v82, 0x3fb8aa3b, v82
	v_exp_f32_e32 v82, v82
	v_add_u32_e32 v110, s3, v110
	v_sub_u32_e32 v79, 0x7f, v110
	v_cvt_f32_u32_e32 v79, v79
	v_mul_f32_e64 v79, v79, -v108
	v_mul_f32_e32 v79, 0x3fb8aa3b, v79
	v_exp_f32_e32 v79, v79
	v_cvt_f32_u32_e32 v83, v110
	v_mul_f32_e64 v83, v83, -v109
	v_mul_f32_e32 v83, 0x3fb8aa3b, v83
	v_exp_f32_e32 v83, v83
	s_add_u32 s4, s4, s21
	s_addc_u32 s5, s5, 0
	global_load_dwordx4 v[100:103], v90, s[4:5]
	global_load_dwordx4 v[104:107], v90, s[4:5] offset:16
	s_waitcnt vmcnt(2)
	v_mul_f32_e32 v108, v164, v64
	v_mul_f32_e32 v109, v164, v65
	v_mul_f32_e32 v110, v164, v66
	v_mul_f32_e32 v111, v164, v67
	v_mul_f32_e32 v112, v164, v60
	v_mul_f32_e32 v113, v164, v61
	v_mul_f32_e32 v114, v164, v62
	v_mul_f32_e32 v115, v164, v63
	v_mul_f32_e32 v91, v93, v109
	v_mul_f32_e32 v116, v93, v108
	v_fma_f32 v108, v92, v108, -v91
	v_fma_f32 v109, v92, v109, v116
	v_mul_f32_e32 v91, v95, v111
	v_mul_f32_e32 v116, v95, v110
	v_fma_f32 v110, v94, v110, -v91
	v_fma_f32 v111, v94, v111, v116
	v_mul_f32_e32 v91, v97, v113
	v_mul_f32_e32 v116, v97, v112
	v_fma_f32 v112, v96, v112, -v91
	v_fma_f32 v113, v96, v113, v116
	v_mul_f32_e32 v91, v99, v115
	v_mul_f32_e32 v116, v99, v114
	v_fma_f32 v114, v98, v114, -v91
	v_fma_f32 v115, v98, v115, v116
	v_cvt_pk_bf16_f32 v120, v108, v109
	v_cvt_pk_bf16_f32 v121, v110, v111
	v_cvt_pk_bf16_f32 v122, v112, v113
	v_cvt_pk_bf16_f32 v123, v114, v115
	global_store_dwordx4 v89, v[120:123], s[16:17]
	s_add_u32 s16, s16, 0x4000
	s_addc_u32 s17, s17, 0
	v_mul_f32_e32 v91, v76, v108
	v_mul_f32_e32 v116, v76, v109
	v_cvt_pk_bf16_f32 v124, v91, v116
	v_mul_f32_e32 v91, v76, v110
	v_mul_f32_e32 v116, v76, v111
	v_cvt_pk_bf16_f32 v125, v91, v116
	v_mul_f32_e32 v91, v76, v112
	v_mul_f32_e32 v116, v76, v113
	v_cvt_pk_bf16_f32 v126, v91, v116
	v_mul_f32_e32 v91, v76, v114
	v_mul_f32_e32 v116, v76, v115
	v_cvt_pk_bf16_f32 v127, v91, v116
	ds_write_b128 v84, v[124:127]
	v_mul_f32_e32 v91, v80, v108
	v_mul_f32_e32 v116, v80, v109
	v_cvt_pk_bf16_f32 v128, v91, v116
	v_mul_f32_e32 v91, v80, v110
	v_mul_f32_e32 v116, v80, v111
	v_cvt_pk_bf16_f32 v129, v91, v116
	v_mul_f32_e32 v91, v80, v112
	v_mul_f32_e32 v116, v80, v113
	v_cvt_pk_bf16_f32 v130, v91, v116
	v_mul_f32_e32 v91, v80, v114
	v_mul_f32_e32 v116, v80, v115
	v_cvt_pk_bf16_f32 v131, v91, v116
	s_add_u32 s4, s4, s21
	s_addc_u32 s5, s5, 0
	global_load_dwordx4 v[92:95], v90, s[4:5]
	global_load_dwordx4 v[96:99], v90, s[4:5] offset:16
	s_waitcnt vmcnt(3)
	v_mul_f32_e32 v108, v165, v56
	v_mul_f32_e32 v109, v165, v57
	v_mul_f32_e32 v110, v165, v58
	v_mul_f32_e32 v111, v165, v59
	v_mul_f32_e32 v112, v165, v52
	v_mul_f32_e32 v113, v165, v53
	v_mul_f32_e32 v114, v165, v54
	v_mul_f32_e32 v115, v165, v55
	v_mul_f32_e32 v91, v101, v109
	v_mul_f32_e32 v116, v101, v108
	v_fma_f32 v108, v100, v108, -v91
	v_fma_f32 v109, v100, v109, v116
	v_mul_f32_e32 v91, v103, v111
	v_mul_f32_e32 v116, v103, v110
	v_fma_f32 v110, v102, v110, -v91
	v_fma_f32 v111, v102, v111, v116
	v_mul_f32_e32 v91, v105, v113
	v_mul_f32_e32 v116, v105, v112
	v_fma_f32 v112, v104, v112, -v91
	v_fma_f32 v113, v104, v113, v116
	v_mul_f32_e32 v91, v107, v115
	v_mul_f32_e32 v116, v107, v114
	v_fma_f32 v114, v106, v114, -v91
	v_fma_f32 v115, v106, v115, v116
	v_cvt_pk_bf16_f32 v120, v108, v109
	v_cvt_pk_bf16_f32 v121, v110, v111
	v_cvt_pk_bf16_f32 v122, v112, v113
	v_cvt_pk_bf16_f32 v123, v114, v115
	global_store_dwordx4 v89, v[120:123], s[16:17]
	s_add_u32 s16, s16, 0x4000
	s_addc_u32 s17, s17, 0
	v_mul_f32_e32 v91, v77, v108
	v_mul_f32_e32 v116, v77, v109
	v_cvt_pk_bf16_f32 v124, v91, v116
	v_mul_f32_e32 v91, v77, v110
	v_mul_f32_e32 v116, v77, v111
	v_cvt_pk_bf16_f32 v125, v91, v116
	v_mul_f32_e32 v91, v77, v112
	v_mul_f32_e32 v116, v77, v113
	v_cvt_pk_bf16_f32 v126, v91, v116
	v_mul_f32_e32 v91, v77, v114
	v_mul_f32_e32 v116, v77, v115
	v_cvt_pk_bf16_f32 v127, v91, v116
	ds_write_b128 v84, v[124:127] offset:1024
	v_mul_f32_e32 v91, v81, v108
	v_mul_f32_e32 v116, v81, v109
	v_cvt_pk_bf16_f32 v132, v91, v116
	v_mul_f32_e32 v91, v81, v110
	v_mul_f32_e32 v116, v81, v111
	v_cvt_pk_bf16_f32 v133, v91, v116
	v_mul_f32_e32 v91, v81, v112
	v_mul_f32_e32 v116, v81, v113
	v_cvt_pk_bf16_f32 v134, v91, v116
	v_mul_f32_e32 v91, v81, v114
	v_mul_f32_e32 v116, v81, v115
	v_cvt_pk_bf16_f32 v135, v91, v116
	ds_read_b64_tr_b16 v[120:121], v85
	ds_read_b64_tr_b16 v[122:123], v85 offset:256
	ds_read_b64_tr_b16 v[124:125], v86
	ds_read_b64_tr_b16 v[126:127], v86 offset:256
	s_waitcnt lgkmcnt(0)
	global_store_dwordx4 v87, v[120:123], s[36:37]
	global_store_dwordx4 v88, v[124:127], s[36:37]
	ds_write_b128 v84, v[128:131]
	ds_write_b128 v84, v[132:135] offset:1024
	s_nop 1
	ds_read_b64_tr_b16 v[120:121], v85
	ds_read_b64_tr_b16 v[122:123], v85 offset:256
	ds_read_b64_tr_b16 v[124:125], v86
	ds_read_b64_tr_b16 v[126:127], v86 offset:256
	s_waitcnt lgkmcnt(0)
	global_store_dwordx4 v87, v[120:123], s[40:41]
	global_store_dwordx4 v88, v[124:127], s[40:41]
	s_add_u32 s36, s36, s43
	s_addc_u32 s37, s37, 0
	s_add_u32 s40, s40, s43
	s_addc_u32 s41, s41, 0
	s_add_u32 s4, s4, s21
	s_addc_u32 s5, s5, 0
	global_load_dwordx4 v[100:103], v90, s[4:5]
	global_load_dwordx4 v[104:107], v90, s[4:5] offset:16
	s_waitcnt vmcnt(7)
	v_mul_f32_e32 v108, v166, v48
	v_mul_f32_e32 v109, v166, v49
	v_mul_f32_e32 v110, v166, v50
	v_mul_f32_e32 v111, v166, v51
	v_mul_f32_e32 v112, v166, v44
	v_mul_f32_e32 v113, v166, v45
	v_mul_f32_e32 v114, v166, v46
	v_mul_f32_e32 v115, v166, v47
	v_mul_f32_e32 v91, v93, v109
	v_mul_f32_e32 v116, v93, v108
	v_fma_f32 v108, v92, v108, -v91
	v_fma_f32 v109, v92, v109, v116
	v_mul_f32_e32 v91, v95, v111
	v_mul_f32_e32 v116, v95, v110
	v_fma_f32 v110, v94, v110, -v91
	v_fma_f32 v111, v94, v111, v116
	v_mul_f32_e32 v91, v97, v113
	v_mul_f32_e32 v116, v97, v112
	v_fma_f32 v112, v96, v112, -v91
	v_fma_f32 v113, v96, v113, v116
	v_mul_f32_e32 v91, v99, v115
	v_mul_f32_e32 v116, v99, v114
	v_fma_f32 v114, v98, v114, -v91
	v_fma_f32 v115, v98, v115, v116
	v_cvt_pk_bf16_f32 v120, v108, v109
	v_cvt_pk_bf16_f32 v121, v110, v111
	v_cvt_pk_bf16_f32 v122, v112, v113
	v_cvt_pk_bf16_f32 v123, v114, v115
	global_store_dwordx4 v89, v[120:123], s[16:17]
	s_add_u32 s16, s16, 0x4000
	s_addc_u32 s17, s17, 0
	v_mul_f32_e32 v91, v78, v108
	v_mul_f32_e32 v116, v78, v109
	v_cvt_pk_bf16_f32 v124, v91, v116
	v_mul_f32_e32 v91, v78, v110
	v_mul_f32_e32 v116, v78, v111
	v_cvt_pk_bf16_f32 v125, v91, v116
	v_mul_f32_e32 v91, v78, v112
	v_mul_f32_e32 v116, v78, v113
	v_cvt_pk_bf16_f32 v126, v91, v116
	v_mul_f32_e32 v91, v78, v114
	v_mul_f32_e32 v116, v78, v115
	v_cvt_pk_bf16_f32 v127, v91, v116
	ds_write_b128 v84, v[124:127]
	v_mul_f32_e32 v91, v82, v108
	v_mul_f32_e32 v116, v82, v109
	v_cvt_pk_bf16_f32 v128, v91, v116
	v_mul_f32_e32 v91, v82, v110
	v_mul_f32_e32 v116, v82, v111
	v_cvt_pk_bf16_f32 v129, v91, v116
	v_mul_f32_e32 v91, v82, v112
	v_mul_f32_e32 v116, v82, v113
	v_cvt_pk_bf16_f32 v130, v91, v116
	v_mul_f32_e32 v91, v82, v114
	v_mul_f32_e32 v116, v82, v115
	v_cvt_pk_bf16_f32 v131, v91, v116
	s_add_u32 s4, s4, 0x5000
	s_addc_u32 s5, s5, 0
	global_load_dwordx4 v[92:95], v90, s[4:5]
	global_load_dwordx4 v[96:99], v90, s[4:5] offset:16
	s_waitcnt vmcnt(3)
	v_mul_f32_e32 v108, v167, v40
	v_mul_f32_e32 v109, v167, v41
	v_mul_f32_e32 v110, v167, v42
	v_mul_f32_e32 v111, v167, v43
	v_mul_f32_e32 v112, v167, v36
	v_mul_f32_e32 v113, v167, v37
	v_mul_f32_e32 v114, v167, v38
	v_mul_f32_e32 v115, v167, v39
	v_mul_f32_e32 v91, v101, v109
	v_mul_f32_e32 v116, v101, v108
	v_fma_f32 v108, v100, v108, -v91
	v_fma_f32 v109, v100, v109, v116
	v_mul_f32_e32 v91, v103, v111
	v_mul_f32_e32 v116, v103, v110
	v_fma_f32 v110, v102, v110, -v91
	v_fma_f32 v111, v102, v111, v116
	v_mul_f32_e32 v91, v105, v113
	v_mul_f32_e32 v116, v105, v112
	v_fma_f32 v112, v104, v112, -v91
	v_fma_f32 v113, v104, v113, v116
	v_mul_f32_e32 v91, v107, v115
	v_mul_f32_e32 v116, v107, v114
	v_fma_f32 v114, v106, v114, -v91
	v_fma_f32 v115, v106, v115, v116
	v_cvt_pk_bf16_f32 v120, v108, v109
	v_cvt_pk_bf16_f32 v121, v110, v111
	v_cvt_pk_bf16_f32 v122, v112, v113
	v_cvt_pk_bf16_f32 v123, v114, v115
	global_store_dwordx4 v89, v[120:123], s[16:17]
	s_add_u32 s16, s16, 0x14000
	s_addc_u32 s17, s17, 0
	v_mul_f32_e32 v91, v79, v108
	v_mul_f32_e32 v116, v79, v109
	v_cvt_pk_bf16_f32 v124, v91, v116
	v_mul_f32_e32 v91, v79, v110
	v_mul_f32_e32 v116, v79, v111
	v_cvt_pk_bf16_f32 v125, v91, v116
	v_mul_f32_e32 v91, v79, v112
	v_mul_f32_e32 v116, v79, v113
	v_cvt_pk_bf16_f32 v126, v91, v116
	v_mul_f32_e32 v91, v79, v114
	v_mul_f32_e32 v116, v79, v115
	v_cvt_pk_bf16_f32 v127, v91, v116
	ds_write_b128 v84, v[124:127] offset:1024
	v_mul_f32_e32 v91, v83, v108
	v_mul_f32_e32 v116, v83, v109
	v_cvt_pk_bf16_f32 v132, v91, v116
	v_mul_f32_e32 v91, v83, v110
	v_mul_f32_e32 v116, v83, v111
	v_cvt_pk_bf16_f32 v133, v91, v116
	v_mul_f32_e32 v91, v83, v112
	v_mul_f32_e32 v116, v83, v113
	v_cvt_pk_bf16_f32 v134, v91, v116
	v_mul_f32_e32 v91, v83, v114
	v_mul_f32_e32 v116, v83, v115
	v_cvt_pk_bf16_f32 v135, v91, v116
	ds_read_b64_tr_b16 v[120:121], v85
	ds_read_b64_tr_b16 v[122:123], v85 offset:256
	ds_read_b64_tr_b16 v[124:125], v86
	ds_read_b64_tr_b16 v[126:127], v86 offset:256
	s_waitcnt lgkmcnt(0)
	global_store_dwordx4 v87, v[120:123], s[36:37]
	global_store_dwordx4 v88, v[124:127], s[36:37]
	ds_write_b128 v84, v[128:131]
	ds_write_b128 v84, v[132:135] offset:1024
	s_nop 1
	ds_read_b64_tr_b16 v[120:121], v85
	ds_read_b64_tr_b16 v[122:123], v85 offset:256
	ds_read_b64_tr_b16 v[124:125], v86
	ds_read_b64_tr_b16 v[126:127], v86 offset:256
	s_waitcnt lgkmcnt(0)
	global_store_dwordx4 v87, v[120:123], s[40:41]
	global_store_dwordx4 v88, v[124:127], s[40:41]
	s_add_u32 s36, s36, 0xc0
	s_addc_u32 s37, s37, 0
	s_add_u32 s40, s40, 0xc0
	s_addc_u32 s41, s41, 0
	s_cmp_eq_u32 s48, 64
	s_cbranch_scc1 .Lsec1_b_done
	s_add_u32 s4, s4, s21
	s_addc_u32 s5, s5, 0
	global_load_dwordx4 v[100:103], v90, s[4:5]
	global_load_dwordx4 v[104:107], v90, s[4:5] offset:16
	s_waitcnt vmcnt(7)
	v_mul_f32_e32 v108, v246, v32
	v_mul_f32_e32 v109, v246, v33
	v_mul_f32_e32 v110, v246, v34
	v_mul_f32_e32 v111, v246, v35
	v_mul_f32_e32 v112, v246, v28
	v_mul_f32_e32 v113, v246, v29
	v_mul_f32_e32 v114, v246, v30
	v_mul_f32_e32 v115, v246, v31
	v_mul_f32_e32 v91, v93, v109
	v_mul_f32_e32 v116, v93, v108
	v_fma_f32 v108, v92, v108, -v91
	v_fma_f32 v109, v92, v109, v116
	v_mul_f32_e32 v91, v95, v111
	v_mul_f32_e32 v116, v95, v110
	v_fma_f32 v110, v94, v110, -v91
	v_fma_f32 v111, v94, v111, v116
	v_mul_f32_e32 v91, v97, v113
	v_mul_f32_e32 v116, v97, v112
	v_fma_f32 v112, v96, v112, -v91
	v_fma_f32 v113, v96, v113, v116
	v_mul_f32_e32 v91, v99, v115
	v_mul_f32_e32 v116, v99, v114
	v_fma_f32 v114, v98, v114, -v91
	v_fma_f32 v115, v98, v115, v116
	v_cvt_pk_bf16_f32 v120, v108, v109
	v_cvt_pk_bf16_f32 v121, v110, v111
	v_cvt_pk_bf16_f32 v122, v112, v113
	v_cvt_pk_bf16_f32 v123, v114, v115
	global_store_dwordx4 v89, v[120:123], s[16:17]
	s_add_u32 s16, s16, 0x4000
	s_addc_u32 s17, s17, 0
	v_mul_f32_e32 v91, v76, v108
	v_mul_f32_e32 v116, v76, v109
	v_cvt_pk_bf16_f32 v124, v91, v116
	v_mul_f32_e32 v91, v76, v110
	v_mul_f32_e32 v116, v76, v111
	v_cvt_pk_bf16_f32 v125, v91, v116
	v_mul_f32_e32 v91, v76, v112
	v_mul_f32_e32 v116, v76, v113
	v_cvt_pk_bf16_f32 v126, v91, v116
	v_mul_f32_e32 v91, v76, v114
	v_mul_f32_e32 v116, v76, v115
	v_cvt_pk_bf16_f32 v127, v91, v116
	ds_write_b128 v84, v[124:127]
	v_mul_f32_e32 v91, v80, v108
	v_mul_f32_e32 v116, v80, v109
	v_cvt_pk_bf16_f32 v128, v91, v116
	v_mul_f32_e32 v91, v80, v110
	v_mul_f32_e32 v116, v80, v111
	v_cvt_pk_bf16_f32 v129, v91, v116
	v_mul_f32_e32 v91, v80, v112
	v_mul_f32_e32 v116, v80, v113
	v_cvt_pk_bf16_f32 v130, v91, v116
	v_mul_f32_e32 v91, v80, v114
	v_mul_f32_e32 v116, v80, v115
	v_cvt_pk_bf16_f32 v131, v91, v116
	s_add_u32 s4, s4, s21
	s_addc_u32 s5, s5, 0
	global_load_dwordx4 v[92:95], v90, s[4:5]
	global_load_dwordx4 v[96:99], v90, s[4:5] offset:16
	s_waitcnt vmcnt(3)
	v_mul_f32_e32 v108, v247, v24
	v_mul_f32_e32 v109, v247, v25
	v_mul_f32_e32 v110, v247, v26
	v_mul_f32_e32 v111, v247, v27
	v_mul_f32_e32 v112, v247, v20
	v_mul_f32_e32 v113, v247, v21
	v_mul_f32_e32 v114, v247, v22
	v_mul_f32_e32 v115, v247, v23
	v_mul_f32_e32 v91, v101, v109
	v_mul_f32_e32 v116, v101, v108
	v_fma_f32 v108, v100, v108, -v91
	v_fma_f32 v109, v100, v109, v116
	v_mul_f32_e32 v91, v103, v111
	v_mul_f32_e32 v116, v103, v110
	v_fma_f32 v110, v102, v110, -v91
	v_fma_f32 v111, v102, v111, v116
	v_mul_f32_e32 v91, v105, v113
	v_mul_f32_e32 v116, v105, v112
	v_fma_f32 v112, v104, v112, -v91
	v_fma_f32 v113, v104, v113, v116
	v_mul_f32_e32 v91, v107, v115
	v_mul_f32_e32 v116, v107, v114
	v_fma_f32 v114, v106, v114, -v91
	v_fma_f32 v115, v106, v115, v116
	v_cvt_pk_bf16_f32 v120, v108, v109
	v_cvt_pk_bf16_f32 v121, v110, v111
	v_cvt_pk_bf16_f32 v122, v112, v113
	v_cvt_pk_bf16_f32 v123, v114, v115
	global_store_dwordx4 v89, v[120:123], s[16:17]
	s_add_u32 s16, s16, 0x4000
	s_addc_u32 s17, s17, 0
	v_mul_f32_e32 v91, v77, v108
	v_mul_f32_e32 v116, v77, v109
	v_cvt_pk_bf16_f32 v124, v91, v116
	v_mul_f32_e32 v91, v77, v110
	v_mul_f32_e32 v116, v77, v111
	v_cvt_pk_bf16_f32 v125, v91, v116
	v_mul_f32_e32 v91, v77, v112
	v_mul_f32_e32 v116, v77, v113
	v_cvt_pk_bf16_f32 v126, v91, v116
	v_mul_f32_e32 v91, v77, v114
	v_mul_f32_e32 v116, v77, v115
	v_cvt_pk_bf16_f32 v127, v91, v116
	ds_write_b128 v84, v[124:127] offset:1024
	v_mul_f32_e32 v91, v81, v108
	v_mul_f32_e32 v116, v81, v109
	v_cvt_pk_bf16_f32 v132, v91, v116
	v_mul_f32_e32 v91, v81, v110
	v_mul_f32_e32 v116, v81, v111
	v_cvt_pk_bf16_f32 v133, v91, v116
	v_mul_f32_e32 v91, v81, v112
	v_mul_f32_e32 v116, v81, v113
	v_cvt_pk_bf16_f32 v134, v91, v116
	v_mul_f32_e32 v91, v81, v114
	v_mul_f32_e32 v116, v81, v115
	v_cvt_pk_bf16_f32 v135, v91, v116
	ds_read_b64_tr_b16 v[120:121], v85
	ds_read_b64_tr_b16 v[122:123], v85 offset:256
	ds_read_b64_tr_b16 v[124:125], v86
	ds_read_b64_tr_b16 v[126:127], v86 offset:256
	s_waitcnt lgkmcnt(0)
	global_store_dwordx4 v87, v[120:123], s[36:37]
	global_store_dwordx4 v88, v[124:127], s[36:37]
	ds_write_b128 v84, v[128:131]
	ds_write_b128 v84, v[132:135] offset:1024
	s_nop 1
	ds_read_b64_tr_b16 v[120:121], v85
	ds_read_b64_tr_b16 v[122:123], v85 offset:256
	ds_read_b64_tr_b16 v[124:125], v86
	ds_read_b64_tr_b16 v[126:127], v86 offset:256
	s_waitcnt lgkmcnt(0)
	global_store_dwordx4 v87, v[120:123], s[40:41]
	global_store_dwordx4 v88, v[124:127], s[40:41]
	s_add_u32 s36, s36, 64
	s_addc_u32 s37, s37, 0
	s_add_u32 s40, s40, 64
	s_addc_u32 s41, s41, 0
	s_add_u32 s4, s4, s21
	s_addc_u32 s5, s5, 0
	global_load_dwordx4 v[100:103], v90, s[4:5]
	global_load_dwordx4 v[104:107], v90, s[4:5] offset:16
	s_waitcnt vmcnt(7)
	v_mul_f32_e32 v108, v248, v16
	v_mul_f32_e32 v109, v248, v17
	v_mul_f32_e32 v110, v248, v18
	v_mul_f32_e32 v111, v248, v19
	v_mul_f32_e32 v112, v248, v12
	v_mul_f32_e32 v113, v248, v13
	v_mul_f32_e32 v114, v248, v14
	v_mul_f32_e32 v115, v248, v15
	v_mul_f32_e32 v91, v93, v109
	v_mul_f32_e32 v116, v93, v108
	v_fma_f32 v108, v92, v108, -v91
	v_fma_f32 v109, v92, v109, v116
	v_mul_f32_e32 v91, v95, v111
	v_mul_f32_e32 v116, v95, v110
	v_fma_f32 v110, v94, v110, -v91
	v_fma_f32 v111, v94, v111, v116
	v_mul_f32_e32 v91, v97, v113
	v_mul_f32_e32 v116, v97, v112
	v_fma_f32 v112, v96, v112, -v91
	v_fma_f32 v113, v96, v113, v116
	v_mul_f32_e32 v91, v99, v115
	v_mul_f32_e32 v116, v99, v114
	v_fma_f32 v114, v98, v114, -v91
	v_fma_f32 v115, v98, v115, v116
	v_cvt_pk_bf16_f32 v120, v108, v109
	v_cvt_pk_bf16_f32 v121, v110, v111
	v_cvt_pk_bf16_f32 v122, v112, v113
	v_cvt_pk_bf16_f32 v123, v114, v115
	global_store_dwordx4 v89, v[120:123], s[16:17]
	s_add_u32 s16, s16, 0x4000
	s_addc_u32 s17, s17, 0
	v_mul_f32_e32 v91, v78, v108
	v_mul_f32_e32 v116, v78, v109
	v_cvt_pk_bf16_f32 v124, v91, v116
	v_mul_f32_e32 v91, v78, v110
	v_mul_f32_e32 v116, v78, v111
	v_cvt_pk_bf16_f32 v125, v91, v116
	v_mul_f32_e32 v91, v78, v112
	v_mul_f32_e32 v116, v78, v113
	v_cvt_pk_bf16_f32 v126, v91, v116
	v_mul_f32_e32 v91, v78, v114
	v_mul_f32_e32 v116, v78, v115
	v_cvt_pk_bf16_f32 v127, v91, v116
	ds_write_b128 v84, v[124:127]
	v_mul_f32_e32 v91, v82, v108
	v_mul_f32_e32 v116, v82, v109
	v_cvt_pk_bf16_f32 v128, v91, v116
	v_mul_f32_e32 v91, v82, v110
	v_mul_f32_e32 v116, v82, v111
	v_cvt_pk_bf16_f32 v129, v91, v116
	v_mul_f32_e32 v91, v82, v112
	v_mul_f32_e32 v116, v82, v113
	v_cvt_pk_bf16_f32 v130, v91, v116
	v_mul_f32_e32 v91, v82, v114
	v_mul_f32_e32 v116, v82, v115
	v_cvt_pk_bf16_f32 v131, v91, v116
	s_waitcnt vmcnt(1)
	v_mul_f32_e32 v108, v249, v8
	v_mul_f32_e32 v109, v249, v9
	v_mul_f32_e32 v110, v249, v10
	v_mul_f32_e32 v111, v249, v11
	v_mul_f32_e32 v112, v249, v4
	v_mul_f32_e32 v113, v249, v5
	v_mul_f32_e32 v114, v249, v6
	v_mul_f32_e32 v115, v249, v7
	v_mul_f32_e32 v91, v101, v109
	v_mul_f32_e32 v116, v101, v108
	v_fma_f32 v108, v100, v108, -v91
	v_fma_f32 v109, v100, v109, v116
	v_mul_f32_e32 v91, v103, v111
	v_mul_f32_e32 v116, v103, v110
	v_fma_f32 v110, v102, v110, -v91
	v_fma_f32 v111, v102, v111, v116
	v_mul_f32_e32 v91, v105, v113
	v_mul_f32_e32 v116, v105, v112
	v_fma_f32 v112, v104, v112, -v91
	v_fma_f32 v113, v104, v113, v116
	v_mul_f32_e32 v91, v107, v115
	v_mul_f32_e32 v116, v107, v114
	v_fma_f32 v114, v106, v114, -v91
	v_fma_f32 v115, v106, v115, v116
	v_cvt_pk_bf16_f32 v120, v108, v109
	v_cvt_pk_bf16_f32 v121, v110, v111
	v_cvt_pk_bf16_f32 v122, v112, v113
	v_cvt_pk_bf16_f32 v123, v114, v115
	global_store_dwordx4 v89, v[120:123], s[16:17]
	s_add_u32 s16, s16, 0x14000
	s_addc_u32 s17, s17, 0
	v_mul_f32_e32 v91, v79, v108
	v_mul_f32_e32 v116, v79, v109
	v_cvt_pk_bf16_f32 v124, v91, v116
	v_mul_f32_e32 v91, v79, v110
	v_mul_f32_e32 v116, v79, v111
	v_cvt_pk_bf16_f32 v125, v91, v116
	v_mul_f32_e32 v91, v79, v112
	v_mul_f32_e32 v116, v79, v113
	v_cvt_pk_bf16_f32 v126, v91, v116
	v_mul_f32_e32 v91, v79, v114
	v_mul_f32_e32 v116, v79, v115
	v_cvt_pk_bf16_f32 v127, v91, v116
	ds_write_b128 v84, v[124:127] offset:1024
	v_mul_f32_e32 v91, v83, v108
	v_mul_f32_e32 v116, v83, v109
	v_cvt_pk_bf16_f32 v132, v91, v116
	v_mul_f32_e32 v91, v83, v110
	v_mul_f32_e32 v116, v83, v111
	v_cvt_pk_bf16_f32 v133, v91, v116
	v_mul_f32_e32 v91, v83, v112
	v_mul_f32_e32 v116, v83, v113
	v_cvt_pk_bf16_f32 v134, v91, v116
	v_mul_f32_e32 v91, v83, v114
	v_mul_f32_e32 v116, v83, v115
	v_cvt_pk_bf16_f32 v135, v91, v116
	ds_read_b64_tr_b16 v[120:121], v85
	ds_read_b64_tr_b16 v[122:123], v85 offset:256
	ds_read_b64_tr_b16 v[124:125], v86
	ds_read_b64_tr_b16 v[126:127], v86 offset:256
	s_waitcnt lgkmcnt(0)
	global_store_dwordx4 v87, v[120:123], s[36:37]
	global_store_dwordx4 v88, v[124:127], s[36:37]
	ds_write_b128 v84, v[128:131]
	ds_write_b128 v84, v[132:135] offset:1024
	s_nop 1
	ds_read_b64_tr_b16 v[120:121], v85
	ds_read_b64_tr_b16 v[122:123], v85 offset:256
	ds_read_b64_tr_b16 v[124:125], v86
	ds_read_b64_tr_b16 v[126:127], v86 offset:256
	s_waitcnt lgkmcnt(0)
	global_store_dwordx4 v87, v[120:123], s[40:41]
	global_store_dwordx4 v88, v[124:127], s[40:41]
